# MIXA step: memory K/V image staged first, then waves 0-3 run conv then memory-attention units while waves 4-7 run units then conv (memory-bound and MFMA-bound parts overlap per SIMD)
# baseline (speedup 1.0000x reference)
.LBB0_342:
	s_and_b64 vcc, exec, s[6:7]
	s_cbranch_vccz .LBB0_359
	s_movk_i32 s4, 0x800
	v_cmp_gt_i32_e32 vcc, s4, v130
	s_and_saveexec_b64 s[6:7], vcc
	s_cbranch_execz .LBB0_353
	s_lshl_b32 s4, s40, 18
	s_add_u32 s4, s84, s4
	v_readlane_b32 s8, v254, 7
	s_addc_u32 s5, s85, 0
	s_lshl_b32 s8, s8, 1
	s_add_u32 s4, s4, s8
	v_readlane_b32 s8, v254, 9
	s_addc_u32 s5, s5, 0
	s_lshl_b32 s8, s8, 1
	s_add_u32 s4, s4, s8
	v_lshlrev_b32_e32 v5, 4, v130
	s_addc_u32 s5, s5, 0
	v_and_b32_e32 v134, 0x70, v5
	s_waitcnt lgkmcnt(0)
	v_lshl_add_u64 v[2:3], s[4:5], 0, v[134:135]
	v_add_u32_e32 v4, 0, v134
	v_ashrrev_i32_e32 v12, 3, v130
	v_mov_b32_e32 v13, 0
	v_lshlrev_b64 v[8:9], 9, v[12:13]
	v_lshl_add_u64 v[8:9], v[2:3], 0, v[8:9]
	v_mad_u32_u24 v226, v12, s29, v4
	s_mov_b64 s[8:9], 0x8000
	global_load_dwordx4 v[178:181], v[8:9], off
	v_lshl_add_u64 v[8:9], v[8:9], 0, s[8:9]
	global_load_dwordx4 v[182:185], v[8:9], off
	v_lshl_add_u64 v[8:9], v[8:9], 0, s[8:9]
	global_load_dwordx4 v[186:189], v[8:9], off
	v_lshl_add_u64 v[8:9], v[8:9], 0, s[8:9]
	global_load_dwordx4 v[190:193], v[8:9], off
	s_lshl_b32 s4, s35, 18
	v_readlane_b32 s5, v254, 8
	s_or_b32 s4, s4, s5
	s_add_u32 s4, s31, s4
	s_addc_u32 s5, s59, 0
	v_readlane_b32 s8, v254, 10
	s_add_u32 s4, s4, s8
	s_addc_u32 s5, s5, 0
	v_and_b32_e32 v134, 0x1f0, v5
	v_lshl_add_u64 v[2:3], s[4:5], 0, v[134:135]
	v_add_u32_e32 v4, 0, v134
	v_ashrrev_i32_e32 v10, 5, v130
	v_mov_b32_e32 v11, 0
	v_lshlrev_b64 v[6:7], 9, v[10:11]
	v_lshl_add_u64 v[6:7], v[2:3], 0, v[6:7]
	v_mad_u32_u24 v227, v10, s36, v4
	s_mov_b64 s[8:9], 0x2000
	global_load_dwordx4 v[194:197], v[6:7], off
	v_lshl_add_u64 v[6:7], v[6:7], 0, s[8:9]
	global_load_dwordx4 v[198:201], v[6:7], off
	v_lshl_add_u64 v[6:7], v[6:7], 0, s[8:9]
	global_load_dwordx4 v[202:205], v[6:7], off
	v_lshl_add_u64 v[6:7], v[6:7], 0, s[8:9]
	global_load_dwordx4 v[206:209], v[6:7], off
	s_waitcnt vmcnt(7)
	ds_write_b128 v226, v[178:181]
	s_waitcnt vmcnt(6)
	ds_write_b128 v226, v[182:185] offset:9216
	s_waitcnt vmcnt(5)
	ds_write_b128 v226, v[186:189] offset:18432
	s_waitcnt vmcnt(4)
	ds_write_b128 v226, v[190:193] offset:27648
	s_waitcnt vmcnt(3)
	ds_write_b128 v227, v[194:197] offset:36864
	s_waitcnt vmcnt(2)
	ds_write_b128 v227, v[198:201] offset:45312
	s_waitcnt vmcnt(1)
	ds_write_b128 v227, v[202:205] offset:53760
	s_waitcnt vmcnt(0)
	ds_write_b128 v227, v[206:209] offset:62208
.LBB0_353:
	s_or_b64 exec, exec, s[6:7]
	s_waitcnt vmcnt(0) lgkmcnt(0)
	s_barrier
	v_writelane_b32 v253, 0, 1
	s_cmp_gt_u32 s38, 3
	s_cbranch_scc1 .Lmx_units
.Lmx_conv:
	v_readlane_b32 s4, v254, 13
	s_nop 1
	v_add_u32_e32 v35, s4, v130
	s_mov_b32 s4, 0x60000
	v_cmp_gt_i32_e32 vcc, s4, v35
	s_and_saveexec_b64 s[6:7], vcc
	s_cbranch_execz .LBB0_348
	s_load_dwordx2 s[4:5], s[88:89], 0x28
	s_add_u32 s8, s82, 0xf200000
	s_mul_i32 s10, s35, 0x2400
	s_addc_u32 s9, s83, 0
	v_lshlrev_b32_e32 v34, 3, v35
	s_waitcnt lgkmcnt(0)
	s_add_u32 s10, s4, s10
	s_addc_u32 s11, s5, 0
	s_add_u32 s88, s10, 0x1800
	s_addc_u32 s89, s11, 0
	s_lshl_b32 s4, s63, 3
	s_mov_b64 s[90:91], 0
	s_branch .LBB0_346

.LBB0_348:
	s_or_b64 exec, exec, s[6:7]
	s_branch .Lmx_after
.Lmx_units:
	s_add_i32 s6, s38, s75
	s_cmpk_gt_i32 s6, 0x1ff
	s_cbranch_scc1 .Lmx_after
	v_readlane_b32 s4, v254, 9
	s_lshl_b32 s7, s4, 1
	s_add_u32 s4, s82, s7
	v_and_b32_e32 v6, 31, v130
	s_addc_u32 s5, s83, 0
	v_lshrrev_b32_e32 v4, 5, v158
	v_lshlrev_b32_e32 v134, 9, v6
	v_lshl_add_u64 v[2:3], s[4:5], 0, v[134:135]
	v_lshlrev_b32_e32 v134, 3, v4
	v_lshlrev_b32_e32 v4, 4, v4
	v_mov_b32_e32 v5, v135
	v_lshl_add_u64 v[2:3], v[2:3], 0, v[4:5]
	s_mov_b64 s[4:5], 0x12200000
	v_cmp_lt_i32_e32 vcc, v177, v171
	v_lshl_add_u64 v[66:67], v[2:3], 0, s[4:5]
	s_add_u32 s4, s86, s7
	v_cndmask_b32_e32 v2, v170, v177, vcc
	v_lshlrev_b32_e32 v70, 2, v2
	v_or_b32_e32 v2, 32, v158
	v_mul_u32_u24_e32 v7, 0x210, v2
	s_addc_u32 s5, s87, 0
	v_lshlrev_b32_e32 v2, 11, v6
	v_mov_b32_e32 v3, v135
	v_lshl_add_u64 v[2:3], s[4:5], 0, v[2:3]
	v_mul_u32_u24_e32 v5, 0x210, v6
	v_lshl_add_u64 v[68:69], v[2:3], 0, v[134:135]
	v_or_b32_e32 v2, v7, v134
	v_readlane_b32 s4, v254, 63
	s_nop 1
	v_add_u32_e32 v71, s4, v2
	v_or_b32_e32 v2, v5, v134
	v_add_u32_e32 v72, s4, v2
	v_mul_u32_u24_e32 v2, 0x90, v6
	v_add3_u32 v73, v2, v4, 0

.Lmx_after:
	v_readlane_b32 s4, v253, 1
	s_cmp_lg_u32 s4, 0
	s_cbranch_scc1 .LBB0_358
	v_writelane_b32 v253, 1, 1
	s_cmp_gt_u32 s38, 3
	s_cbranch_scc1 .Lmx_conv
	s_branch .Lmx_units
